# up-projection: the epilogue's 8 per-row sum-of-squares loads are issued in the last K-loop iteration (third counted wait of that iteration allows 8 more outstanding)
# speedup vs baseline: 1.0037x; 1.0003x over previous
.LBB0_534:
	s_add_u32 s46, s44, 0xfffc0080
	s_addc_u32 s47, s45, -1
	s_add_i32 s75, 0, 0x10000
	s_cmp_eq_u32 s74, 12
	s_cselect_b32 s49, s1, s47
	s_cselect_b32 s48, s56, s46
	s_cselect_b32 s47, s7, s51
	s_cselect_b32 s46, s57, s50
	s_add_i32 s80, 0, 0x14000
	v_add_u32_e32 v138, s75, v198
	v_add_u32_e32 v142, s80, v198
	ds_read_b128 v[126:129], v138
	ds_read_b128 v[130:133], v138 offset:1024
	ds_read_b128 v[134:137], v138 offset:2048
	ds_read_b128 v[138:141], v138 offset:3072
	ds_read_b128 v[148:151], v142
	ds_read_b128 v[152:155], v142 offset:1024
	ds_read_b128 v[166:169], v142 offset:2048
	ds_read_b128 v[170:173], v142 offset:3072
	v_lshl_add_u64 v[142:143], s[44:45], 0, v[162:163]
	s_add_i32 m0, s65, 0xc000
	ds_read_b128 v[174:177], v199
	ds_read_b128 v[178:181], v199 offset:1024
	ds_read_b128 v[182:185], v199 offset:2048
	ds_read_b128 v[186:189], v199 offset:3072
	ds_read_b128 v[190:193], v199 offset:4096
	ds_read_b128 v[200:203], v199 offset:5120
	ds_read_b128 v[204:207], v199 offset:6144
	ds_read_b128 v[208:211], v199 offset:7168
	global_load_lds_dwordx4 v[142:143], off
	v_lshl_add_u64 v[142:143], s[44:45], 0, v[164:165]
	s_add_i32 m0, s65, 0xe000
	s_nop 0
	global_load_lds_dwordx4 v[142:143], off
	s_waitcnt vmcnt(8)
	s_waitcnt lgkmcnt(0)
	s_barrier
	s_setprio 1
	s_waitcnt lgkmcnt(0)
	v_mfma_f32_16x16x32_bf16 v[102:105], v[126:129], v[174:177], v[102:105]
	v_mfma_f32_16x16x32_bf16 v[78:81], v[134:137], v[174:177], v[78:81]
	v_mfma_f32_16x16x32_bf16 v[142:145], v[126:129], v[182:185], v[144:147]
	v_mfma_f32_16x16x32_bf16 v[90:93], v[134:137], v[182:185], v[90:93]
	v_mfma_f32_16x16x32_bf16 v[110:113], v[126:129], v[190:193], v[110:113]
	v_mfma_f32_16x16x32_bf16 v[82:85], v[134:137], v[190:193], v[82:85]
	v_mfma_f32_16x16x32_bf16 v[114:117], v[126:129], v[204:207], v[114:117]
	v_mfma_f32_16x16x32_bf16 v[70:73], v[134:137], v[204:207], v[70:73]
	v_mfma_f32_16x16x32_bf16 v[102:105], v[130:133], v[178:181], v[102:105]
	v_mfma_f32_16x16x32_bf16 v[78:81], v[138:141], v[178:181], v[78:81]
	v_mfma_f32_16x16x32_bf16 v[142:145], v[130:133], v[186:189], v[142:145]
	v_mfma_f32_16x16x32_bf16 v[90:93], v[138:141], v[186:189], v[90:93]
	v_mfma_f32_16x16x32_bf16 v[110:113], v[130:133], v[200:203], v[110:113]
	v_mfma_f32_16x16x32_bf16 v[82:85], v[138:141], v[200:203], v[82:85]
	v_mfma_f32_16x16x32_bf16 v[114:117], v[130:133], v[208:211], v[114:117]
	v_mfma_f32_16x16x32_bf16 v[70:73], v[138:141], v[208:211], v[70:73]
	s_setprio 0
	s_setprio 1
	v_mfma_f32_16x16x32_bf16 v[118:121], v[148:151], v[174:177], v[118:121]
	v_mfma_f32_16x16x32_bf16 v[86:89], v[166:169], v[174:177], v[86:89]
	v_mfma_f32_16x16x32_bf16 v[106:109], v[148:151], v[182:185], v[106:109]
	v_mfma_f32_16x16x32_bf16 v[74:77], v[166:169], v[182:185], v[74:77]
	v_mfma_f32_16x16x32_bf16 v[98:101], v[148:151], v[190:193], v[98:101]
	v_mfma_f32_16x16x32_bf16 v[66:69], v[166:169], v[190:193], v[66:69]
	v_mfma_f32_16x16x32_bf16 v[94:97], v[148:151], v[204:207], v[94:97]
	v_mfma_f32_16x16x32_bf16 v[62:65], v[166:169], v[204:207], v[62:65]
	v_mfma_f32_16x16x32_bf16 v[118:121], v[152:155], v[178:181], v[118:121]
	v_mfma_f32_16x16x32_bf16 v[86:89], v[170:173], v[178:181], v[86:89]
	v_mfma_f32_16x16x32_bf16 v[106:109], v[152:155], v[186:189], v[106:109]
	v_mfma_f32_16x16x32_bf16 v[74:77], v[170:173], v[186:189], v[74:77]
	v_mfma_f32_16x16x32_bf16 v[98:101], v[152:155], v[200:203], v[98:101]
	v_mfma_f32_16x16x32_bf16 v[66:69], v[170:173], v[200:203], v[66:69]
	v_mfma_f32_16x16x32_bf16 v[94:97], v[152:155], v[208:211], v[94:97]
	v_mfma_f32_16x16x32_bf16 v[62:65], v[170:173], v[208:211], v[62:65]
	s_setprio 0
	s_barrier
	s_add_i32 s75, s75, s64
	v_lshl_add_u64 v[194:195], s[46:47], 0, v[0:1]
	s_mov_b32 m0, s75
	ds_read_b128 v[174:177], v199 offset:16384
	ds_read_b128 v[178:181], v199 offset:17408
	ds_read_b128 v[182:185], v199 offset:18432
	ds_read_b128 v[186:189], v199 offset:19456
	ds_read_b128 v[190:193], v199 offset:20480
	ds_read_b128 v[200:203], v199 offset:21504
	ds_read_b128 v[204:207], v199 offset:22528
	ds_read_b128 v[208:211], v199 offset:23552
	global_load_lds_dwordx4 v[194:195], off
	s_add_i32 m0, s75, 0x2000
	s_add_u32 s78, s46, 0x40000
	v_lshl_add_u64 v[212:213], s[46:47], 0, v[156:157]
	s_addc_u32 s79, s47, 0
	s_add_i32 s75, s80, s64
	global_load_lds_dwordx4 v[212:213], off
	v_lshl_add_u64 v[146:147], s[78:79], 0, v[0:1]
	s_mov_b32 m0, s75
	v_lshl_add_u64 v[216:217], s[48:49], 0, v[160:161]
	global_load_lds_dwordx4 v[146:147], off
	v_lshl_add_u64 v[146:147], s[78:79], 0, v[156:157]
	s_add_i32 m0, s75, 0x2000
	v_lshl_add_u64 v[218:219], s[48:49], 0, v[158:159]
	global_load_lds_dwordx4 v[146:147], off
	s_mov_b32 m0, s65
	s_nop 0
	global_load_lds_dwordx4 v[216:217], off
	s_mov_b32 m0, s66
	s_nop 0
	global_load_lds_dwordx4 v[218:219], off
	s_waitcnt vmcnt(8)
	s_cmp_eq_u32 s74, 12
	s_cbranch_scc0 .Lp4rq_skip
	v_add_u32_e32 v230, s58, v196
	v_lshl_add_u32 v230, s76, 8, v230
	v_ashrrev_i32_e32 v231, 31, v230
	v_lshl_add_u64 v[230:231], v[230:231], 2, s[24:25]
	global_load_dword v223, v[230:231], off
	global_load_dword v224, v[230:231], off offset:192
	global_load_dword v225, v[230:231], off offset:512
	global_load_dword v226, v[230:231], off offset:704
	global_load_dword v227, v[230:231], off offset:64
	global_load_dword v228, v[230:231], off offset:576
	global_load_dword v229, v[230:231], off offset:640
	global_load_dword v232, v[230:231], off offset:128
.Lp4rq_skip:
	s_waitcnt lgkmcnt(0)
	s_barrier
	s_setprio 1
	s_waitcnt lgkmcnt(0)
	v_mfma_f32_16x16x32_bf16 v[122:125], v[126:129], v[174:177], v[122:125]
	v_mfma_f32_16x16x32_bf16 v[42:45], v[134:137], v[174:177], v[42:45]
	v_mfma_f32_16x16x32_bf16 v[58:61], v[126:129], v[182:185], v[58:61]
	v_mfma_f32_16x16x32_bf16 v[26:29], v[134:137], v[182:185], v[26:29]
	v_mfma_f32_16x16x32_bf16 v[46:49], v[126:129], v[190:193], v[46:49]
	v_mfma_f32_16x16x32_bf16 v[14:17], v[134:137], v[190:193], v[14:17]
	v_mfma_f32_16x16x32_bf16 v[54:57], v[126:129], v[204:207], v[54:57]
	v_mfma_f32_16x16x32_bf16 v[18:21], v[134:137], v[204:207], v[18:21]
	v_mfma_f32_16x16x32_bf16 v[122:125], v[130:133], v[178:181], v[122:125]
	v_mfma_f32_16x16x32_bf16 v[42:45], v[138:141], v[178:181], v[42:45]
	v_mfma_f32_16x16x32_bf16 v[58:61], v[130:133], v[186:189], v[58:61]
	v_mfma_f32_16x16x32_bf16 v[26:29], v[138:141], v[186:189], v[26:29]
	v_mfma_f32_16x16x32_bf16 v[46:49], v[130:133], v[200:203], v[46:49]
	v_mfma_f32_16x16x32_bf16 v[14:17], v[138:141], v[200:203], v[14:17]
	v_mfma_f32_16x16x32_bf16 v[54:57], v[130:133], v[208:211], v[54:57]
	v_mfma_f32_16x16x32_bf16 v[18:21], v[138:141], v[208:211], v[18:21]
	s_setprio 0
	s_setprio 1
	v_mfma_f32_16x16x32_bf16 v[50:53], v[148:151], v[174:177], v[50:53]
	v_mfma_f32_16x16x32_bf16 v[22:25], v[166:169], v[174:177], v[22:25]
	v_mfma_f32_16x16x32_bf16 v[38:41], v[148:151], v[182:185], v[38:41]
	v_mfma_f32_16x16x32_bf16 v[10:13], v[166:169], v[182:185], v[10:13]
	v_mfma_f32_16x16x32_bf16 v[34:37], v[148:151], v[190:193], v[34:37]
	v_mfma_f32_16x16x32_bf16 v[6:9], v[166:169], v[190:193], v[6:9]
	v_mfma_f32_16x16x32_bf16 v[30:33], v[148:151], v[204:207], v[30:33]
	v_mfma_f32_16x16x32_bf16 v[2:5], v[166:169], v[204:207], v[2:5]
	v_mfma_f32_16x16x32_bf16 v[50:53], v[152:155], v[178:181], v[50:53]
	v_mfma_f32_16x16x32_bf16 v[22:25], v[170:173], v[178:181], v[22:25]
	v_mfma_f32_16x16x32_bf16 v[38:41], v[152:155], v[186:189], v[38:41]
	v_mfma_f32_16x16x32_bf16 v[10:13], v[170:173], v[186:189], v[10:13]
	v_mfma_f32_16x16x32_bf16 v[34:37], v[152:155], v[200:203], v[34:37]
	v_mfma_f32_16x16x32_bf16 v[6:9], v[170:173], v[200:203], v[6:9]
	v_mfma_f32_16x16x32_bf16 v[30:33], v[152:155], v[208:211], v[30:33]
	v_mfma_f32_16x16x32_bf16 v[2:5], v[170:173], v[208:211], v[2:5]
	s_setprio 0
	s_barrier
	s_add_i32 s75, 0, 0x18000
	s_add_i32 s78, 0, 0x1c000
	v_add_u32_e32 v138, s75, v198
	v_add_u32_e32 v146, s78, v198
	ds_read_b128 v[126:129], v138
	ds_read_b128 v[130:133], v138 offset:1024
	ds_read_b128 v[134:137], v138 offset:2048
	ds_read_b128 v[138:141], v138 offset:3072
	ds_read_b128 v[148:151], v146
	ds_read_b128 v[152:155], v146 offset:1024
	ds_read_b128 v[166:169], v146 offset:2048
	ds_read_b128 v[170:173], v146 offset:3072
	s_add_u32 s48, s48, 0x40000
	s_addc_u32 s49, s49, 0
	s_mov_b32 m0, s67
	v_lshl_add_u64 v[146:147], s[48:49], 0, v[160:161]
	ds_read_b128 v[174:177], v199 offset:32768
	ds_read_b128 v[178:181], v199 offset:33792
	ds_read_b128 v[182:185], v199 offset:34816
	ds_read_b128 v[186:189], v199 offset:35840
	ds_read_b128 v[190:193], v199 offset:36864
	ds_read_b128 v[200:203], v199 offset:37888
	ds_read_b128 v[204:207], v199 offset:38912
	ds_read_b128 v[208:211], v199 offset:39936
	global_load_lds_dwordx4 v[146:147], off
	v_lshl_add_u64 v[146:147], s[48:49], 0, v[158:159]
	s_mov_b32 m0, s68
	s_nop 0
	global_load_lds_dwordx4 v[146:147], off
	s_cmp_eq_u32 s74, 12
	s_cbranch_scc1 .Lp4rq_w16
	s_waitcnt vmcnt(8)
	s_branch .Lp4rq_wj
.Lp4rq_w16:
	s_waitcnt vmcnt(16)
.Lp4rq_wj:
	s_waitcnt lgkmcnt(0)
	s_barrier
	s_setprio 1
	s_waitcnt lgkmcnt(0)
	v_mfma_f32_16x16x32_bf16 v[102:105], v[126:129], v[174:177], v[102:105]
	v_mfma_f32_16x16x32_bf16 v[78:81], v[134:137], v[174:177], v[78:81]
	v_mfma_f32_16x16x32_bf16 v[142:145], v[126:129], v[182:185], v[142:145]
	v_mfma_f32_16x16x32_bf16 v[90:93], v[134:137], v[182:185], v[90:93]
	v_mfma_f32_16x16x32_bf16 v[110:113], v[126:129], v[190:193], v[110:113]
	v_mfma_f32_16x16x32_bf16 v[82:85], v[134:137], v[190:193], v[82:85]
	v_mfma_f32_16x16x32_bf16 v[114:117], v[126:129], v[204:207], v[114:117]
	v_mfma_f32_16x16x32_bf16 v[70:73], v[134:137], v[204:207], v[70:73]
	v_mfma_f32_16x16x32_bf16 v[102:105], v[130:133], v[178:181], v[102:105]
	v_mfma_f32_16x16x32_bf16 v[78:81], v[138:141], v[178:181], v[78:81]
	v_mfma_f32_16x16x32_bf16 v[144:147], v[130:133], v[186:189], v[142:145]
	v_mfma_f32_16x16x32_bf16 v[90:93], v[138:141], v[186:189], v[90:93]
	v_mfma_f32_16x16x32_bf16 v[110:113], v[130:133], v[200:203], v[110:113]
	v_mfma_f32_16x16x32_bf16 v[82:85], v[138:141], v[200:203], v[82:85]
	v_mfma_f32_16x16x32_bf16 v[114:117], v[130:133], v[208:211], v[114:117]
	v_mfma_f32_16x16x32_bf16 v[70:73], v[138:141], v[208:211], v[70:73]
	s_setprio 0
	s_setprio 1
	v_mfma_f32_16x16x32_bf16 v[118:121], v[148:151], v[174:177], v[118:121]
	v_mfma_f32_16x16x32_bf16 v[86:89], v[166:169], v[174:177], v[86:89]
	v_mfma_f32_16x16x32_bf16 v[106:109], v[148:151], v[182:185], v[106:109]
	v_mfma_f32_16x16x32_bf16 v[74:77], v[166:169], v[182:185], v[74:77]
	v_mfma_f32_16x16x32_bf16 v[98:101], v[148:151], v[190:193], v[98:101]
	v_mfma_f32_16x16x32_bf16 v[66:69], v[166:169], v[190:193], v[66:69]
	v_mfma_f32_16x16x32_bf16 v[94:97], v[148:151], v[204:207], v[94:97]
	v_mfma_f32_16x16x32_bf16 v[62:65], v[166:169], v[204:207], v[62:65]
	v_mfma_f32_16x16x32_bf16 v[118:121], v[152:155], v[178:181], v[118:121]
	v_mfma_f32_16x16x32_bf16 v[86:89], v[170:173], v[178:181], v[86:89]
	v_mfma_f32_16x16x32_bf16 v[106:109], v[152:155], v[186:189], v[106:109]
	v_mfma_f32_16x16x32_bf16 v[74:77], v[170:173], v[186:189], v[74:77]
	v_mfma_f32_16x16x32_bf16 v[98:101], v[152:155], v[200:203], v[98:101]
	v_mfma_f32_16x16x32_bf16 v[66:69], v[170:173], v[200:203], v[66:69]
	v_mfma_f32_16x16x32_bf16 v[94:97], v[152:155], v[208:211], v[94:97]
	v_mfma_f32_16x16x32_bf16 v[62:65], v[170:173], v[208:211], v[62:65]
	s_setprio 0
	s_barrier
	s_add_i32 s48, s75, s64
	v_lshl_add_u64 v[142:143], v[194:195], 0, s[28:29]
	s_mov_b32 m0, s48
	ds_read_b128 v[174:177], v199 offset:49152
	ds_read_b128 v[178:181], v199 offset:50176
	ds_read_b128 v[182:185], v199 offset:51200
	ds_read_b128 v[186:189], v199 offset:52224
	ds_read_b128 v[190:193], v199 offset:53248
	ds_read_b128 v[200:203], v199 offset:54272
	ds_read_b128 v[204:207], v199 offset:55296
	ds_read_b128 v[208:211], v199 offset:56320
	global_load_lds_dwordx4 v[142:143], off
	s_add_i32 m0, s48, 0x2000
	s_add_u32 s46, s46, 0x40080
	v_lshl_add_u64 v[142:143], v[212:213], 0, s[28:29]
	s_addc_u32 s47, s47, 0
	s_add_i32 s48, s78, s64
	global_load_lds_dwordx4 v[142:143], off
	v_lshl_add_u64 v[142:143], s[46:47], 0, v[0:1]
	s_mov_b32 m0, s48
	s_nop 0
	global_load_lds_dwordx4 v[142:143], off
	v_lshl_add_u64 v[142:143], s[46:47], 0, v[156:157]
	s_add_i32 m0, s48, 0x2000
	s_nop 0
	global_load_lds_dwordx4 v[142:143], off
	v_lshl_add_u64 v[142:143], v[216:217], 0, s[28:29]
	s_mov_b32 m0, s9
	s_nop 0
	global_load_lds_dwordx4 v[142:143], off
	v_lshl_add_u64 v[142:143], v[218:219], 0, s[28:29]
	s_mov_b32 m0, s10
	s_nop 0
	global_load_lds_dwordx4 v[142:143], off
	s_waitcnt vmcnt(8)
	s_waitcnt lgkmcnt(0)
	s_barrier
	s_setprio 1
	s_waitcnt lgkmcnt(0)
	v_mfma_f32_16x16x32_bf16 v[122:125], v[126:129], v[174:177], v[122:125]
	v_mfma_f32_16x16x32_bf16 v[42:45], v[134:137], v[174:177], v[42:45]
	v_mfma_f32_16x16x32_bf16 v[58:61], v[126:129], v[182:185], v[58:61]
	v_mfma_f32_16x16x32_bf16 v[26:29], v[134:137], v[182:185], v[26:29]
	v_mfma_f32_16x16x32_bf16 v[46:49], v[126:129], v[190:193], v[46:49]
	v_mfma_f32_16x16x32_bf16 v[14:17], v[134:137], v[190:193], v[14:17]
	v_mfma_f32_16x16x32_bf16 v[54:57], v[126:129], v[204:207], v[54:57]
	v_mfma_f32_16x16x32_bf16 v[18:21], v[134:137], v[204:207], v[18:21]
	v_mfma_f32_16x16x32_bf16 v[122:125], v[130:133], v[178:181], v[122:125]
	v_mfma_f32_16x16x32_bf16 v[42:45], v[138:141], v[178:181], v[42:45]
	v_mfma_f32_16x16x32_bf16 v[58:61], v[130:133], v[186:189], v[58:61]
	v_mfma_f32_16x16x32_bf16 v[26:29], v[138:141], v[186:189], v[26:29]
	v_mfma_f32_16x16x32_bf16 v[46:49], v[130:133], v[200:203], v[46:49]
	v_mfma_f32_16x16x32_bf16 v[14:17], v[138:141], v[200:203], v[14:17]
	v_mfma_f32_16x16x32_bf16 v[54:57], v[130:133], v[208:211], v[54:57]
	v_mfma_f32_16x16x32_bf16 v[18:21], v[138:141], v[208:211], v[18:21]
	s_setprio 0
	s_setprio 1
	v_mfma_f32_16x16x32_bf16 v[50:53], v[148:151], v[174:177], v[50:53]
	v_mfma_f32_16x16x32_bf16 v[22:25], v[166:169], v[174:177], v[22:25]
	v_mfma_f32_16x16x32_bf16 v[38:41], v[148:151], v[182:185], v[38:41]
	v_mfma_f32_16x16x32_bf16 v[10:13], v[166:169], v[182:185], v[10:13]
	v_mfma_f32_16x16x32_bf16 v[34:37], v[148:151], v[190:193], v[34:37]
	v_mfma_f32_16x16x32_bf16 v[6:9], v[166:169], v[190:193], v[6:9]
	v_mfma_f32_16x16x32_bf16 v[30:33], v[148:151], v[204:207], v[30:33]
	v_mfma_f32_16x16x32_bf16 v[2:5], v[166:169], v[204:207], v[2:5]
	v_mfma_f32_16x16x32_bf16 v[50:53], v[152:155], v[178:181], v[50:53]
	v_mfma_f32_16x16x32_bf16 v[22:25], v[170:173], v[178:181], v[22:25]
	v_mfma_f32_16x16x32_bf16 v[38:41], v[152:155], v[186:189], v[38:41]
	v_mfma_f32_16x16x32_bf16 v[10:13], v[170:173], v[186:189], v[10:13]
	v_mfma_f32_16x16x32_bf16 v[34:37], v[152:155], v[200:203], v[34:37]
	v_mfma_f32_16x16x32_bf16 v[6:9], v[170:173], v[200:203], v[6:9]
	v_mfma_f32_16x16x32_bf16 v[30:33], v[152:155], v[208:211], v[30:33]
	v_mfma_f32_16x16x32_bf16 v[2:5], v[170:173], v[208:211], v[2:5]
	s_setprio 0
	s_barrier
	s_add_i32 s74, s74, 2
	s_add_u32 s44, s44, 0x100
	s_addc_u32 s45, s45, 0
	s_add_u32 s50, s50, 0x100
	s_addc_u32 s51, s51, 0
	s_cmp_gt_u32 s74, 13
	s_cbranch_scc0 .LBB0_534
	s_and_b64 vcc, exec, s[26:27]
	s_cbranch_vccz .LBB0_537
	s_barrier

.Lxw0_done:
	v_mov_b32_e32 v179, v197
	v_mov_b32_e32 v178, v196
	s_mov_b64 s[56:57], 0
	v_add_u32_e32 v166, s58, v178
	v_lshl_add_u32 v126, s76, 8, v166
	v_ashrrev_i32_e32 v127, 31, v126
	v_lshl_add_u64 v[126:127], v[126:127], 2, s[24:25]
	v_mov_b32_e32 v128, v223
	v_mov_b32_e32 v129, v224
	v_mov_b32_e32 v130, v225
	v_mov_b32_e32 v131, v226
	v_mov_b32_e32 v180, v227
	v_mov_b32_e32 v208, v228
	v_mov_b32_e32 v207, v229
	v_mov_b32_e32 v209, v232
	v_cmp_lt_i32_e64 s[50:51], 14, v178
	s_waitcnt vmcnt(0)
	v_fmamk_f32 v127, v128, 0x3a800000, v214
	v_fmamk_f32 v126, v129, 0x3a800000, v214
	v_fmamk_f32 v135, v130, 0x3a800000, v214
	v_fmamk_f32 v134, v131, 0x3a800000, v214
	v_cmp_gt_f32_e64 s[48:49], s90, v127
	v_cmp_gt_f32_e64 s[46:47], s90, v126
	v_cmp_gt_f32_e64 s[44:45], s90, v135
	v_cmp_gt_f32_e32 vcc, s90, v134
	s_and_saveexec_b64 s[74:75], s[50:51]
	s_xor_b64 s[74:75], exec, s[74:75]
	s_cbranch_execz .LBB0_541
	v_cmp_eq_u32_e64 s[50:51], 15, v178
	s_and_saveexec_b64 s[78:79], s[50:51]
	s_mov_b64 s[56:57], exec
	s_or_b64 exec, exec, s[78:79]
	s_and_b64 s[56:57], s[56:57], exec
